# y10 + P9 passes as straight-line halves (no parking moves) and LN2 wave sums on DPP
# speedup vs baseline: 1.0239x; 1.0073x over previous
.LpA_kb:
	s_waitcnt vmcnt(0)
	s_cmp_lt_u32 s34, 8
	s_cselect_b64 s[2:3], -1, 0
	s_nop 0
	v_cndmask_b32_e64 v5, v212, v211, s[2:3]
	s_add_i32 s60, s33, 0
	v_readlane_b32 s16, v5, s60
	s_add_i32 s61, s33, 1
	v_readlane_b32 s18, v5, s61
	s_add_i32 s62, s33, 2
	v_readlane_b32 s35, v5, s62
	s_add_i32 s63, s33, 3
	v_readlane_b32 s36, v5, s63
	s_add_i32 s60, s33, 4
	v_readlane_b32 s20, v5, s60
	s_add_i32 s61, s33, 5
	v_readlane_b32 s22, v5, s61
	s_add_i32 s62, s33, 6
	v_readlane_b32 s24, v5, s62
	s_add_i32 s63, s33, 7
	v_readlane_b32 s26, v5, s63
	v_mad_u32_u24 v6, s18, v202, v138
	global_load_dwordx3 v[2:4], v6, s[78:79]
	v_mad_u32_u24 v8, s16, v202, v138
	global_load_dwordx3 v[48:50], v8, s[78:79]
	v_mad_u32_u24 v10, s36, v202, v138
	global_load_dwordx3 v[80:82], v10, s[78:79]
	v_mad_u32_u24 v12, s35, v202, v138
	global_load_dwordx3 v[54:56], v12, s[78:79]
	v_mad_u32_u24 v6, s22, v202, v138
	global_load_dwordx3 v[84:86], v6, s[78:79]
	v_mad_u32_u24 v8, s20, v202, v138
	global_load_dwordx3 v[60:62], v8, s[78:79]
	v_mad_u32_u24 v10, s24, v202, v138
	global_load_dwordx3 v[76:78], v10, s[78:79]
	v_mad_u32_u24 v12, s26, v202, v138
	global_load_dwordx3 v[88:90], v12, s[78:79]
	s_add_i32 s60, s33, 8
	v_readlane_b32 s16, v5, s60
	s_add_i32 s61, s33, 9
	v_readlane_b32 s18, v5, s61
	s_add_i32 s62, s33, 10
	v_readlane_b32 s35, v5, s62
	s_add_i32 s63, s33, 11
	v_readlane_b32 s36, v5, s63
	s_add_i32 s60, s33, 12
	v_readlane_b32 s20, v5, s60
	s_add_i32 s61, s33, 13
	v_readlane_b32 s22, v5, s61
	s_add_i32 s62, s33, 14
	v_readlane_b32 s24, v5, s62
	s_add_i32 s63, s33, 15
	v_readlane_b32 s26, v5, s63
	v_mad_u32_u24 v6, s16, v202, v138
	global_load_dwordx3 v[34:36], v6, s[78:79]
	v_mad_u32_u24 v8, s18, v202, v138
	global_load_dwordx3 v[44:46], v8, s[78:79]
	v_mad_u32_u24 v10, s35, v202, v138
	global_load_dwordx3 v[66:68], v10, s[78:79]
	v_mad_u32_u24 v12, s36, v202, v138
	global_load_dwordx3 v[40:42], v12, s[78:79]
	v_mad_u32_u24 v6, s20, v202, v138
	global_load_dwordx3 v[98:100], v6, s[78:79]
	v_mad_u32_u24 v8, s22, v202, v138
	global_load_dwordx3 v[72:74], v8, s[78:79]
	v_mad_u32_u24 v10, s24, v202, v138
	global_load_dwordx3 v[130:132], v10, s[78:79]
	v_mad_u32_u24 v12, s26, v202, v138
	global_load_dwordx3 v[104:106], v12, s[78:79]
	s_waitcnt vmcnt(8)
	s_cmp_lt_u32 s34, 8
	s_cselect_b64 s[2:3], -1, 0
	s_waitcnt vmcnt(8)
	s_waitcnt lgkmcnt(0)
	v_mov_b32_e32 v51, v2
	v_mov_b32_e32 v52, v3
	v_mov_b32_e32 v53, v4
	v_cvt_scalef32_pk32_f32_fp6 v[2:33], v[48:53], 1.0
	v_pk_mul_f32 v[108:109], v[232:233], v[2:3]
	v_pk_mul_f32 v[110:111], v[232:233], v[18:19]
	v_pk_fma_f32 v[108:109], v[234:235], v[4:5], v[108:109]
	v_pk_fma_f32 v[110:111], v[234:235], v[20:21], v[110:111]
	v_pk_fma_f32 v[108:109], v[236:237], v[6:7], v[108:109]
	v_pk_fma_f32 v[110:111], v[236:237], v[22:23], v[110:111]
	v_pk_fma_f32 v[108:109], v[238:239], v[8:9], v[108:109]
	v_pk_fma_f32 v[110:111], v[238:239], v[24:25], v[110:111]
	v_pk_fma_f32 v[108:109], v[240:241], v[10:11], v[108:109]
	v_pk_fma_f32 v[110:111], v[240:241], v[26:27], v[110:111]
	v_pk_fma_f32 v[108:109], v[242:243], v[12:13], v[108:109]
	v_pk_fma_f32 v[110:111], v[242:243], v[28:29], v[110:111]
	v_pk_fma_f32 v[108:109], v[244:245], v[14:15], v[108:109]
	v_pk_fma_f32 v[110:111], v[244:245], v[30:31], v[110:111]
	v_pk_fma_f32 v[108:109], v[246:247], v[16:17], v[108:109]
	v_pk_fma_f32 v[110:111], v[246:247], v[32:33], v[110:111]
	s_nop 0
	v_add_f32_e32 v37, v108, v109
	v_add_f32_e32 v38, v110, v111
	v_mov_b32_e32 v57, v80
	v_mov_b32_e32 v58, v81
	v_mov_b32_e32 v59, v82
	v_cvt_scalef32_pk32_f32_fp6 v[2:33], v[54:59], 1.0
	v_pk_mul_f32 v[108:109], v[232:233], v[2:3]
	v_pk_mul_f32 v[110:111], v[232:233], v[18:19]
	v_pk_fma_f32 v[108:109], v[234:235], v[4:5], v[108:109]
	v_pk_fma_f32 v[110:111], v[234:235], v[20:21], v[110:111]
	v_pk_fma_f32 v[108:109], v[236:237], v[6:7], v[108:109]
	v_pk_fma_f32 v[110:111], v[236:237], v[22:23], v[110:111]
	v_pk_fma_f32 v[108:109], v[238:239], v[8:9], v[108:109]
	v_pk_fma_f32 v[110:111], v[238:239], v[24:25], v[110:111]
	v_pk_fma_f32 v[108:109], v[240:241], v[10:11], v[108:109]
	v_pk_fma_f32 v[110:111], v[240:241], v[26:27], v[110:111]
	v_pk_fma_f32 v[108:109], v[242:243], v[12:13], v[108:109]
	v_pk_fma_f32 v[110:111], v[242:243], v[28:29], v[110:111]
	v_pk_fma_f32 v[108:109], v[244:245], v[14:15], v[108:109]
	v_pk_fma_f32 v[110:111], v[244:245], v[30:31], v[110:111]
	v_pk_fma_f32 v[108:109], v[246:247], v[16:17], v[108:109]
	v_pk_fma_f32 v[110:111], v[246:247], v[32:33], v[110:111]
	s_nop 0
	v_add_f32_e32 v39, v108, v109
	v_add_f32_e32 v43, v110, v111
	v_mov_b32_e32 v63, v84
	v_mov_b32_e32 v64, v85
	v_mov_b32_e32 v65, v86
	v_cvt_scalef32_pk32_f32_fp6 v[2:33], v[60:65], 1.0
	v_pk_mul_f32 v[108:109], v[232:233], v[2:3]
	v_pk_mul_f32 v[110:111], v[232:233], v[18:19]
	v_pk_fma_f32 v[108:109], v[234:235], v[4:5], v[108:109]
	v_pk_fma_f32 v[110:111], v[234:235], v[20:21], v[110:111]
	v_pk_fma_f32 v[108:109], v[236:237], v[6:7], v[108:109]
	v_pk_fma_f32 v[110:111], v[236:237], v[22:23], v[110:111]
	v_pk_fma_f32 v[108:109], v[238:239], v[8:9], v[108:109]
	v_pk_fma_f32 v[110:111], v[238:239], v[24:25], v[110:111]
	v_pk_fma_f32 v[108:109], v[240:241], v[10:11], v[108:109]
	v_pk_fma_f32 v[110:111], v[240:241], v[26:27], v[110:111]
	v_pk_fma_f32 v[108:109], v[242:243], v[12:13], v[108:109]
	v_pk_fma_f32 v[110:111], v[242:243], v[28:29], v[110:111]
	v_pk_fma_f32 v[108:109], v[244:245], v[14:15], v[108:109]
	v_pk_fma_f32 v[110:111], v[244:245], v[30:31], v[110:111]
	v_pk_fma_f32 v[108:109], v[246:247], v[16:17], v[108:109]
	v_pk_fma_f32 v[110:111], v[246:247], v[32:33], v[110:111]
	s_nop 0
	v_add_f32_e32 v47, v108, v109
	v_add_f32_e32 v48, v110, v111
	v_mov_b32_e32 v79, v88
	v_mov_b32_e32 v80, v89
	v_mov_b32_e32 v81, v90
	v_cvt_scalef32_pk32_f32_fp6 v[2:33], v[76:81], 1.0
	v_pk_mul_f32 v[108:109], v[232:233], v[2:3]
	v_pk_mul_f32 v[110:111], v[232:233], v[18:19]
	v_pk_fma_f32 v[108:109], v[234:235], v[4:5], v[108:109]
	v_pk_fma_f32 v[110:111], v[234:235], v[20:21], v[110:111]
	v_pk_fma_f32 v[108:109], v[236:237], v[6:7], v[108:109]
	v_pk_fma_f32 v[110:111], v[236:237], v[22:23], v[110:111]
	v_pk_fma_f32 v[108:109], v[238:239], v[8:9], v[108:109]
	v_pk_fma_f32 v[110:111], v[238:239], v[24:25], v[110:111]
	v_pk_fma_f32 v[108:109], v[240:241], v[10:11], v[108:109]
	v_pk_fma_f32 v[110:111], v[240:241], v[26:27], v[110:111]
	v_pk_fma_f32 v[108:109], v[242:243], v[12:13], v[108:109]
	v_pk_fma_f32 v[110:111], v[242:243], v[28:29], v[110:111]
	v_pk_fma_f32 v[108:109], v[244:245], v[14:15], v[108:109]
	v_pk_fma_f32 v[110:111], v[244:245], v[30:31], v[110:111]
	v_pk_fma_f32 v[108:109], v[246:247], v[16:17], v[108:109]
	v_pk_fma_f32 v[110:111], v[246:247], v[32:33], v[110:111]
	s_nop 0
	v_add_f32_e32 v2, v108, v109
	v_add_f32_e32 v18, v110, v111
	v_cndmask_b32_e64 v3, v37, v38, s[0:1]
	v_cndmask_b32_e64 v5, v39, v43, s[0:1]
	v_cndmask_b32_e64 v6, v47, v48, s[0:1]
	v_cndmask_b32_e64 v7, v2, v18, s[0:1]
	v_cndmask_b32_e64 v4, v38, v37, s[0:1]
	s_nop 0
	v_mov_b32_dpp v3, v3 quad_perm:[1,0,3,2] row_mask:0xf bank_mask:0xf
	v_mov_b32_dpp v5, v5 quad_perm:[1,0,3,2] row_mask:0xf bank_mask:0xf
	v_mov_b32_dpp v6, v6 quad_perm:[1,0,3,2] row_mask:0xf bank_mask:0xf
	v_mov_b32_dpp v7, v7 quad_perm:[1,0,3,2] row_mask:0xf bank_mask:0xf
	v_add_f32_e32 v3, v4, v3
	v_cndmask_b32_e64 v4, v43, v39, s[0:1]
	v_add_f32_e32 v4, v4, v5
	v_cndmask_b32_e64 v5, v48, v47, s[0:1]
	v_cndmask_b32_e64 v2, v18, v2, s[0:1]
	v_add_f32_e32 v5, v5, v6
	v_add_f32_e32 v2, v2, v7
	v_cndmask_b32_e32 v6, v3, v4, vcc
	v_cndmask_b32_e32 v7, v5, v2, vcc
	v_cndmask_b32_e32 v3, v4, v3, vcc
	v_cndmask_b32_e32 v2, v2, v5, vcc
	v_and_or_b32 v5, s33, 56, v231
	v_mov_b32_dpp v6, v6 quad_perm:[2,3,0,1] row_mask:0xf bank_mask:0xf
	v_mov_b32_dpp v7, v7 quad_perm:[2,3,0,1] row_mask:0xf bank_mask:0xf
	v_add_f32_e32 v3, v3, v6
	v_add_f32_e32 v2, v2, v7
	v_cndmask_b32_e64 v4, v3, v2, s[4:5]
	v_cndmask_b32_e64 v2, v2, v3, s[4:5]
	v_lshlrev_b32_e32 v5, 2, v5
	v_cndmask_b32_e64 v7, v214, v213, s[2:3]
	v_mov_b32_dpp v6, v4 row_shl:4 row_mask:0xf bank_mask:0x5
	v_mov_b32_dpp v6, v4 row_shr:4 row_mask:0xf bank_mask:0xa
	ds_bpermute_b32 v7, v5, v7
	v_add_f32_e32 v2, v2, v6
	s_nop 1
	v_mov_b32_dpp v3, v2 row_ror:8 row_mask:0xf bank_mask:0xf
	v_add_f32_e32 v2, v2, v3
	ds_bpermute_b32 v3, v209, v2
	s_waitcnt lgkmcnt(0)
	v_add_f32_e32 v3, v2, v3
	v_mov_b32_e32 v2, v7
	v_mov_b32_e32 v4, v3
	s_nop 1
	v_permlane32_swap_b32 v3, v4
	v_add_f32_e32 v3, v3, v4
	v_mul_f32_e32 v3, 0x3caaaaab, v3
	v_mul_f32_e32 v4, 0x3f3504f3, v3
	v_cmp_nlt_f32_e64 s[2:3], |v4|, 1.0
	s_and_saveexec_b64 s[14:15], s[2:3]
	s_xor_b64 s[14:15], exec, s[14:15]
	s_cbranch_execz .LpA1_erf_else
	v_fma_f32 v5, |v4|, s7, v203
	v_fma_f32 v5, |v4|, v5, s13
	v_fma_f32 v5, |v4|, v5, s17
	v_fma_f32 v5, |v4|, v5, s19
	v_fma_f32 v5, |v4|, v5, s21
	v_fma_f32 v5, |v4|, v5, s23
	v_fma_f32 v5, |v4|, v5, |v4|
	v_mul_f32_e32 v6, 0xbfb8aa3b, v5
	v_fma_f32 v7, v5, s25, -v6
	v_rndne_f32_e32 v8, v6
	v_fmac_f32_e32 v7, 0xb2a5705f, v5
	v_sub_f32_e32 v6, v6, v8
	v_add_f32_e32 v6, v6, v7
	v_cvt_i32_f32_e32 v7, v8
	v_exp_f32_e32 v6, v6
	v_cmp_nlt_f32_e64 s[2:3], s27, v5
	v_ldexp_f32 v6, v6, v7
	s_nop 0
	v_cndmask_b32_e64 v6, 0, v6, s[2:3]
	v_cmp_ngt_f32_e64 s[2:3], s28, v5
	s_nop 1
	v_cndmask_b32_e64 v5, v204, v6, s[2:3]
	v_sub_f32_e32 v5, 1.0, v5

.LpA1_erf_join:
	s_or_b64 exec, exec, s[2:3]
	s_waitcnt lgkmcnt(0)
	v_mul_f32_e32 v2, 0.5, v2
	v_mul_f32_e32 v2, v2, v3
	v_bfi_b32 v3, s29, v5, v4
	v_add_f32_e32 v3, 1.0, v3
	v_mul_f32_e32 v2, v2, v3
	v_mul_f32_e32 v107, 0x3e124925, v2
	v_cmp_eq_u32_e64 s[54:55], s34, v248
	s_sub_i32 s53, s34, 8
	v_cmp_eq_u32_e64 s[56:57], s53, v248
	s_nop 1
	v_cndmask_b32_e64 v249, v249, v107, s[54:55]
	v_cndmask_b32_e64 v255, v255, v107, s[56:57]
	s_add_i32 s34, s34, 1
	s_add_i32 s33, s33, 8
	s_waitcnt vmcnt(0)
	s_cmp_lt_u32 s34, 8
	s_cselect_b64 s[2:3], -1, 0
	s_waitcnt vmcnt(8)
	s_waitcnt lgkmcnt(0)
	v_mov_b32_e32 v37, v44
	v_mov_b32_e32 v38, v45
	v_mov_b32_e32 v39, v46
	v_cvt_scalef32_pk32_f32_fp6 v[2:33], v[34:39], 1.0
	v_pk_mul_f32 v[108:109], v[232:233], v[2:3]
	v_pk_mul_f32 v[110:111], v[232:233], v[18:19]
	v_pk_fma_f32 v[108:109], v[234:235], v[4:5], v[108:109]
	v_pk_fma_f32 v[110:111], v[234:235], v[20:21], v[110:111]
	v_pk_fma_f32 v[108:109], v[236:237], v[6:7], v[108:109]
	v_pk_fma_f32 v[110:111], v[236:237], v[22:23], v[110:111]
	v_pk_fma_f32 v[108:109], v[238:239], v[8:9], v[108:109]
	v_pk_fma_f32 v[110:111], v[238:239], v[24:25], v[110:111]
	v_pk_fma_f32 v[108:109], v[240:241], v[10:11], v[108:109]
	v_pk_fma_f32 v[110:111], v[240:241], v[26:27], v[110:111]
	v_pk_fma_f32 v[108:109], v[242:243], v[12:13], v[108:109]
	v_pk_fma_f32 v[110:111], v[242:243], v[28:29], v[110:111]
	v_pk_fma_f32 v[108:109], v[244:245], v[14:15], v[108:109]
	v_pk_fma_f32 v[110:111], v[244:245], v[30:31], v[110:111]
	v_pk_fma_f32 v[108:109], v[246:247], v[16:17], v[108:109]
	v_pk_fma_f32 v[110:111], v[246:247], v[32:33], v[110:111]
	s_nop 0
	v_add_f32_e32 v37, v108, v109
	v_add_f32_e32 v38, v110, v111
	v_mov_b32_e32 v69, v40
	v_mov_b32_e32 v70, v41
	v_mov_b32_e32 v71, v42
	v_cvt_scalef32_pk32_f32_fp6 v[2:33], v[66:71], 1.0
	v_pk_mul_f32 v[108:109], v[232:233], v[2:3]
	v_pk_mul_f32 v[110:111], v[232:233], v[18:19]
	v_pk_fma_f32 v[108:109], v[234:235], v[4:5], v[108:109]
	v_pk_fma_f32 v[110:111], v[234:235], v[20:21], v[110:111]
	v_pk_fma_f32 v[108:109], v[236:237], v[6:7], v[108:109]
	v_pk_fma_f32 v[110:111], v[236:237], v[22:23], v[110:111]
	v_pk_fma_f32 v[108:109], v[238:239], v[8:9], v[108:109]
	v_pk_fma_f32 v[110:111], v[238:239], v[24:25], v[110:111]
	v_pk_fma_f32 v[108:109], v[240:241], v[10:11], v[108:109]
	v_pk_fma_f32 v[110:111], v[240:241], v[26:27], v[110:111]
	v_pk_fma_f32 v[108:109], v[242:243], v[12:13], v[108:109]
	v_pk_fma_f32 v[110:111], v[242:243], v[28:29], v[110:111]
	v_pk_fma_f32 v[108:109], v[244:245], v[14:15], v[108:109]
	v_pk_fma_f32 v[110:111], v[244:245], v[30:31], v[110:111]
	v_pk_fma_f32 v[108:109], v[246:247], v[16:17], v[108:109]
	v_pk_fma_f32 v[110:111], v[246:247], v[32:33], v[110:111]
	s_nop 0
	v_add_f32_e32 v39, v108, v109
	v_add_f32_e32 v43, v110, v111
	v_mov_b32_e32 v101, v72
	v_mov_b32_e32 v102, v73
	v_mov_b32_e32 v103, v74
	v_cvt_scalef32_pk32_f32_fp6 v[2:33], v[98:103], 1.0
	v_pk_mul_f32 v[108:109], v[232:233], v[2:3]
	v_pk_mul_f32 v[110:111], v[232:233], v[18:19]
	v_pk_fma_f32 v[108:109], v[234:235], v[4:5], v[108:109]
	v_pk_fma_f32 v[110:111], v[234:235], v[20:21], v[110:111]
	v_pk_fma_f32 v[108:109], v[236:237], v[6:7], v[108:109]
	v_pk_fma_f32 v[110:111], v[236:237], v[22:23], v[110:111]
	v_pk_fma_f32 v[108:109], v[238:239], v[8:9], v[108:109]
	v_pk_fma_f32 v[110:111], v[238:239], v[24:25], v[110:111]
	v_pk_fma_f32 v[108:109], v[240:241], v[10:11], v[108:109]
	v_pk_fma_f32 v[110:111], v[240:241], v[26:27], v[110:111]
	v_pk_fma_f32 v[108:109], v[242:243], v[12:13], v[108:109]
	v_pk_fma_f32 v[110:111], v[242:243], v[28:29], v[110:111]
	v_pk_fma_f32 v[108:109], v[244:245], v[14:15], v[108:109]
	v_pk_fma_f32 v[110:111], v[244:245], v[30:31], v[110:111]
	v_pk_fma_f32 v[108:109], v[246:247], v[16:17], v[108:109]
	v_pk_fma_f32 v[110:111], v[246:247], v[32:33], v[110:111]
	s_nop 0
	v_add_f32_e32 v47, v108, v109
	v_add_f32_e32 v48, v110, v111
	v_mov_b32_e32 v133, v104
	v_mov_b32_e32 v134, v105
	v_mov_b32_e32 v135, v106
	v_cvt_scalef32_pk32_f32_fp6 v[2:33], v[130:135], 1.0
	v_pk_mul_f32 v[108:109], v[232:233], v[2:3]
	v_pk_mul_f32 v[110:111], v[232:233], v[18:19]
	v_pk_fma_f32 v[108:109], v[234:235], v[4:5], v[108:109]
	v_pk_fma_f32 v[110:111], v[234:235], v[20:21], v[110:111]
	v_pk_fma_f32 v[108:109], v[236:237], v[6:7], v[108:109]
	v_pk_fma_f32 v[110:111], v[236:237], v[22:23], v[110:111]
	v_pk_fma_f32 v[108:109], v[238:239], v[8:9], v[108:109]
	v_pk_fma_f32 v[110:111], v[238:239], v[24:25], v[110:111]
	v_pk_fma_f32 v[108:109], v[240:241], v[10:11], v[108:109]
	v_pk_fma_f32 v[110:111], v[240:241], v[26:27], v[110:111]
	v_pk_fma_f32 v[108:109], v[242:243], v[12:13], v[108:109]
	v_pk_fma_f32 v[110:111], v[242:243], v[28:29], v[110:111]
	v_pk_fma_f32 v[108:109], v[244:245], v[14:15], v[108:109]
	v_pk_fma_f32 v[110:111], v[244:245], v[30:31], v[110:111]
	v_pk_fma_f32 v[108:109], v[246:247], v[16:17], v[108:109]
	v_pk_fma_f32 v[110:111], v[246:247], v[32:33], v[110:111]
	s_nop 0
	v_add_f32_e32 v2, v108, v109
	v_add_f32_e32 v18, v110, v111
	v_cndmask_b32_e64 v3, v37, v38, s[0:1]
	v_cndmask_b32_e64 v5, v39, v43, s[0:1]
	v_cndmask_b32_e64 v6, v47, v48, s[0:1]
	v_cndmask_b32_e64 v7, v2, v18, s[0:1]
	v_cndmask_b32_e64 v4, v38, v37, s[0:1]
	s_nop 0
	v_mov_b32_dpp v3, v3 quad_perm:[1,0,3,2] row_mask:0xf bank_mask:0xf
	v_mov_b32_dpp v5, v5 quad_perm:[1,0,3,2] row_mask:0xf bank_mask:0xf
	v_mov_b32_dpp v6, v6 quad_perm:[1,0,3,2] row_mask:0xf bank_mask:0xf
	v_mov_b32_dpp v7, v7 quad_perm:[1,0,3,2] row_mask:0xf bank_mask:0xf
	v_add_f32_e32 v3, v4, v3
	v_cndmask_b32_e64 v4, v43, v39, s[0:1]
	v_add_f32_e32 v4, v4, v5
	v_cndmask_b32_e64 v5, v48, v47, s[0:1]
	v_cndmask_b32_e64 v2, v18, v2, s[0:1]
	v_add_f32_e32 v5, v5, v6
	v_add_f32_e32 v2, v2, v7
	v_cndmask_b32_e32 v6, v3, v4, vcc
	v_cndmask_b32_e32 v7, v5, v2, vcc
	v_cndmask_b32_e32 v3, v4, v3, vcc
	v_cndmask_b32_e32 v2, v2, v5, vcc
	v_and_or_b32 v5, s33, 56, v231
	v_mov_b32_dpp v6, v6 quad_perm:[2,3,0,1] row_mask:0xf bank_mask:0xf
	v_mov_b32_dpp v7, v7 quad_perm:[2,3,0,1] row_mask:0xf bank_mask:0xf
	v_add_f32_e32 v3, v3, v6
	v_add_f32_e32 v2, v2, v7
	v_cndmask_b32_e64 v4, v3, v2, s[4:5]
	v_cndmask_b32_e64 v2, v2, v3, s[4:5]
	v_lshlrev_b32_e32 v5, 2, v5
	v_cndmask_b32_e64 v7, v214, v213, s[2:3]
	v_mov_b32_dpp v6, v4 row_shl:4 row_mask:0xf bank_mask:0x5
	v_mov_b32_dpp v6, v4 row_shr:4 row_mask:0xf bank_mask:0xa
	ds_bpermute_b32 v7, v5, v7
	v_add_f32_e32 v2, v2, v6
	s_nop 1
	v_mov_b32_dpp v3, v2 row_ror:8 row_mask:0xf bank_mask:0xf
	v_add_f32_e32 v2, v2, v3
	ds_bpermute_b32 v3, v209, v2
	s_waitcnt lgkmcnt(0)
	v_add_f32_e32 v3, v2, v3
	v_mov_b32_e32 v2, v7
	v_mov_b32_e32 v4, v3
	s_nop 1
	v_permlane32_swap_b32 v3, v4
	v_add_f32_e32 v3, v3, v4
	v_mul_f32_e32 v3, 0x3caaaaab, v3
	v_mul_f32_e32 v4, 0x3f3504f3, v3
	v_cmp_nlt_f32_e64 s[2:3], |v4|, 1.0
	s_and_saveexec_b64 s[14:15], s[2:3]
	s_xor_b64 s[14:15], exec, s[14:15]
	s_cbranch_execz .LpA2_erf_else
	v_fma_f32 v5, |v4|, s7, v203
	v_fma_f32 v5, |v4|, v5, s13
	v_fma_f32 v5, |v4|, v5, s17
	v_fma_f32 v5, |v4|, v5, s19
	v_fma_f32 v5, |v4|, v5, s21
	v_fma_f32 v5, |v4|, v5, s23
	v_fma_f32 v5, |v4|, v5, |v4|
	v_mul_f32_e32 v6, 0xbfb8aa3b, v5
	v_fma_f32 v7, v5, s25, -v6
	v_rndne_f32_e32 v8, v6
	v_fmac_f32_e32 v7, 0xb2a5705f, v5
	v_sub_f32_e32 v6, v6, v8
	v_add_f32_e32 v6, v6, v7
	v_cvt_i32_f32_e32 v7, v8
	v_exp_f32_e32 v6, v6
	v_cmp_nlt_f32_e64 s[2:3], s27, v5
	v_ldexp_f32 v6, v6, v7
	s_nop 0
	v_cndmask_b32_e64 v6, 0, v6, s[2:3]
	v_cmp_ngt_f32_e64 s[2:3], s28, v5
	s_nop 1
	v_cndmask_b32_e64 v5, v204, v6, s[2:3]
	v_sub_f32_e32 v5, 1.0, v5

.LpA2_erf_join:
	s_or_b64 exec, exec, s[2:3]
	s_waitcnt lgkmcnt(0)
	v_mul_f32_e32 v2, 0.5, v2
	v_mul_f32_e32 v2, v2, v3
	v_bfi_b32 v3, s29, v5, v4
	v_add_f32_e32 v3, 1.0, v3
	v_mul_f32_e32 v2, v2, v3
	v_mul_f32_e32 v107, 0x3e124925, v2
	v_cmp_eq_u32_e64 s[54:55], s34, v248
	s_sub_i32 s53, s34, 8
	v_cmp_eq_u32_e64 s[56:57], s53, v248
	s_nop 1
	v_cndmask_b32_e64 v249, v249, v107, s[54:55]
	v_cndmask_b32_e64 v255, v255, v107, s[56:57]
	s_add_i32 s34, s34, 1
	s_add_i32 s33, s33, 8
	s_cmpk_lg_i32 s33, 0x80
	s_cbranch_scc1 .LpA_kb
	s_branch .LpA_epi

.LpB_epi:
	ds_write_b32 v137, v178
	ds_write_b32 v183, v179
	ds_write_b32 v184, v176
	ds_write_b32 v185, v177
	ds_write_b32 v186, v174
	ds_write_b32 v187, v175
	ds_write_b32 v188, v172
	ds_write_b32 v189, v173
	ds_write_b32 v190, v170
	ds_write_b32 v191, v171
	ds_write_b32 v192, v168
	ds_write_b32 v193, v169
	ds_write_b32 v194, v166
	ds_write_b32 v195, v167
	ds_write_b32 v196, v180
	ds_write_b32 v197, v181
	v_lshl_add_u64 v[18:19], v[146:147], 0, v[164:165]
	global_load_dwordx4 v[2:5], v[18:19], off
	global_load_dwordx4 v[6:9], v[162:163], off
	global_load_dwordx4 v[10:13], v[18:19], off offset:16
	global_load_dwordx4 v[14:17], v[162:163], off offset:16
	ds_read_b128 v[18:21], v201
	ds_read_b128 v[22:25], v201 offset:16
	ds_read_b128 v[26:29], v201 offset:32
	ds_read_b128 v[30:33], v201 offset:48
	s_waitcnt vmcnt(3)
	v_lshlrev_b32_e32 v34, 16, v2
	s_waitcnt vmcnt(2)
	v_lshlrev_b32_e32 v36, 16, v6
	v_and_b32_e32 v37, 0xffff0000, v6
	v_lshlrev_b32_e32 v6, 16, v7
	v_and_b32_e32 v7, 0xffff0000, v7
	v_lshlrev_b32_e32 v40, 16, v8
	v_and_b32_e32 v41, 0xffff0000, v8
	v_lshlrev_b32_e32 v8, 16, v9
	v_and_b32_e32 v9, 0xffff0000, v9
	v_and_b32_e32 v35, 0xffff0000, v2
	v_lshlrev_b32_e32 v2, 16, v3
	v_and_b32_e32 v3, 0xffff0000, v3
	v_lshlrev_b32_e32 v38, 16, v4
	v_and_b32_e32 v39, 0xffff0000, v4
	v_lshlrev_b32_e32 v4, 16, v5
	v_and_b32_e32 v5, 0xffff0000, v5
	s_waitcnt vmcnt(0)
	v_lshlrev_b32_e32 v44, 16, v14
	v_and_b32_e32 v45, 0xffff0000, v14
	v_lshlrev_b32_e32 v14, 16, v15
	v_and_b32_e32 v15, 0xffff0000, v15
	s_waitcnt lgkmcnt(3)
	v_pk_fma_f32 v[18:19], v[36:37], s[12:13], v[18:19] op_sel_hi:[1,0,1]
	v_pk_fma_f32 v[6:7], v[6:7], s[12:13], v[20:21] op_sel_hi:[1,0,1]
	s_waitcnt lgkmcnt(2)
	v_pk_fma_f32 v[20:21], v[40:41], s[12:13], v[22:23] op_sel_hi:[1,0,1]
	v_pk_fma_f32 v[8:9], v[8:9], s[12:13], v[24:25] op_sel_hi:[1,0,1]
	s_waitcnt lgkmcnt(1)
	v_pk_fma_f32 v[22:23], v[44:45], s[12:13], v[26:27] op_sel_hi:[1,0,1]
	v_pk_fma_f32 v[14:15], v[14:15], s[12:13], v[28:29] op_sel_hi:[1,0,1]
	v_pk_add_f32 v[18:19], v[18:19], v[34:35]
	v_pk_add_f32 v[26:27], v[6:7], v[2:3]
	v_pk_add_f32 v[20:21], v[20:21], v[38:39]
	v_pk_add_f32 v[28:29], v[8:9], v[4:5]
	v_lshlrev_b32_e32 v42, 16, v10
	v_and_b32_e32 v43, 0xffff0000, v10
	v_lshlrev_b32_e32 v10, 16, v11
	v_and_b32_e32 v11, 0xffff0000, v11
	v_lshlrev_b32_e32 v48, 16, v16
	v_and_b32_e32 v49, 0xffff0000, v16
	v_lshlrev_b32_e32 v16, 16, v17
	v_and_b32_e32 v17, 0xffff0000, v17
	v_mov_b32_e32 v2, v18
	v_mov_b32_e32 v3, v27
	v_pk_mov_b32 v[4:5], v[18:19], v[26:27] op_sel:[1,0]
	v_mov_b32_e32 v6, v20
	v_mov_b32_e32 v7, v29
	v_pk_mov_b32 v[8:9], v[20:21], v[28:29] op_sel:[1,0]
	v_lshlrev_b32_e32 v46, 16, v12
	v_and_b32_e32 v47, 0xffff0000, v12
	v_lshlrev_b32_e32 v12, 16, v13
	v_and_b32_e32 v13, 0xffff0000, v13
	s_waitcnt lgkmcnt(0)
	v_pk_fma_f32 v[24:25], v[48:49], s[12:13], v[30:31] op_sel_hi:[1,0,1]
	v_pk_fma_f32 v[16:17], v[16:17], s[12:13], v[32:33] op_sel_hi:[1,0,1]
	v_pk_add_f32 v[22:23], v[22:23], v[42:43]
	v_pk_add_f32 v[10:11], v[14:15], v[10:11]
	v_pk_add_f32 v[2:3], v[2:3], v[4:5]
	v_pk_add_f32 v[4:5], v[6:7], v[8:9]
	v_pk_add_f32 v[14:15], v[24:25], v[46:47]
	v_pk_add_f32 v[12:13], v[16:17], v[12:13]
	v_pk_add_f32 v[16:17], v[22:23], v[22:23] op_sel:[0,1] op_sel_hi:[1,0]
	v_pk_add_f32 v[24:25], v[10:11], v[10:11] op_sel:[1,0] op_sel_hi:[0,1]
	v_add_f32_e32 v6, v2, v3
	v_pk_add_f32 v[2:3], v[4:5], v[4:5] op_sel:[0,1] op_sel_hi:[1,0]
	v_mov_b32_e32 v31, v14
	v_add_f32_e32 v30, 0, v6
	v_mov_b32_e32 v3, v15
	v_mov_b32_e32 v17, v13
	v_mov_b32_e32 v25, v12
	v_pk_add_f32 v[2:3], v[30:31], v[2:3]
	v_pk_add_f32 v[4:5], v[16:17], v[24:25]
	s_nop 0
	v_pk_add_f32 v[2:3], v[2:3], v[4:5]
	s_nop 0
	v_add_f32_e32 v2, v2, v3
	s_nop 1
	v_add_f32_dpp v2, v2, v2 quad_perm:[1,0,3,2] row_mask:0xf bank_mask:0xf bound_ctrl:1
	s_nop 1
	v_add_f32_dpp v2, v2, v2 quad_perm:[2,3,0,1] row_mask:0xf bank_mask:0xf bound_ctrl:1
	s_nop 1
	v_add_f32_dpp v2, v2, v2 row_half_mirror row_mask:0xf bank_mask:0xf bound_ctrl:1
	s_nop 1
	v_add_f32_dpp v2, v2, v2 row_mirror row_mask:0xf bank_mask:0xf bound_ctrl:1
	s_nop 1
	v_add_f32_dpp v2, v2, v2 row_bcast:15 row_mask:0xa bank_mask:0xf
	s_nop 1
	v_add_f32_dpp v2, v2, v2 row_bcast:31 row_mask:0xc bank_mask:0xf
	s_nop 1
	v_readlane_b32 s53, v2, 63
	global_load_dwordx4 v[2:5], v[156:157], off
	global_load_dwordx4 v[6:9], v[158:159], off
	v_mov_b32_e32 v16, s53
	v_mul_f32_e32 v16, 0x3a800000, v16
	v_pk_add_f32 v[18:19], v[18:19], v[16:17] op_sel_hi:[1,0] neg_lo:[0,1] neg_hi:[0,1]
	v_pk_add_f32 v[24:25], v[26:27], v[16:17] op_sel_hi:[1,0] neg_lo:[0,1] neg_hi:[0,1]
	v_pk_add_f32 v[20:21], v[20:21], v[16:17] op_sel_hi:[1,0] neg_lo:[0,1] neg_hi:[0,1]
	v_pk_add_f32 v[26:27], v[28:29], v[16:17] op_sel_hi:[1,0] neg_lo:[0,1] neg_hi:[0,1]
	v_pk_add_f32 v[22:23], v[22:23], v[16:17] op_sel_hi:[1,0] neg_lo:[0,1] neg_hi:[0,1]
	v_pk_add_f32 v[10:11], v[10:11], v[16:17] op_sel_hi:[1,0] neg_lo:[0,1] neg_hi:[0,1]
	v_pk_add_f32 v[14:15], v[14:15], v[16:17] op_sel_hi:[1,0] neg_lo:[0,1] neg_hi:[0,1]
	v_pk_add_f32 v[12:13], v[12:13], v[16:17] op_sel_hi:[1,0] neg_lo:[0,1] neg_hi:[0,1]
	v_pk_mul_f32 v[16:17], v[18:19], v[18:19]
	v_pk_mul_f32 v[28:29], v[24:25], v[24:25]
	v_add_f32_e32 v16, v16, v17
	v_add_f32_e32 v16, v28, v16
	v_pk_mul_f32 v[30:31], v[20:21], v[20:21]
	v_add_f32_e32 v16, v29, v16
	v_add_f32_e32 v16, v30, v16
	v_pk_mul_f32 v[32:33], v[26:27], v[26:27]
	v_add_f32_e32 v16, v31, v16
	v_add_f32_e32 v16, v32, v16
	v_pk_mul_f32 v[34:35], v[22:23], v[22:23]
	v_add_f32_e32 v16, v33, v16
	v_add_f32_e32 v16, v34, v16
	v_pk_mul_f32 v[36:37], v[10:11], v[10:11]
	v_add_f32_e32 v16, v35, v16
	v_add_f32_e32 v16, v36, v16
	v_pk_mul_f32 v[38:39], v[14:15], v[14:15]
	v_add_f32_e32 v16, v37, v16
	v_add_f32_e32 v16, v38, v16
	v_pk_mul_f32 v[40:41], v[12:13], v[12:13]
	v_add_f32_e32 v16, v39, v16
	v_add_f32_e32 v16, v40, v16
	v_add_f32_e32 v16, v41, v16
	s_nop 1
	v_add_f32_dpp v16, v16, v16 quad_perm:[1,0,3,2] row_mask:0xf bank_mask:0xf bound_ctrl:1
	s_nop 1
	v_add_f32_dpp v16, v16, v16 quad_perm:[2,3,0,1] row_mask:0xf bank_mask:0xf bound_ctrl:1
	s_nop 1
	v_add_f32_dpp v16, v16, v16 row_half_mirror row_mask:0xf bank_mask:0xf bound_ctrl:1
	s_nop 1
	v_add_f32_dpp v16, v16, v16 row_mirror row_mask:0xf bank_mask:0xf bound_ctrl:1
	s_nop 1
	v_add_f32_dpp v16, v16, v16 row_bcast:15 row_mask:0xa bank_mask:0xf
	s_nop 1
	v_add_f32_dpp v16, v16, v16 row_bcast:31 row_mask:0xc bank_mask:0xf
	s_nop 1
	v_readlane_b32 s53, v16, 63
	s_nop 3
	v_mov_b32_e32 v16, s53
	v_fmamk_f32 v16, v16, 0x3a800000, v149
	v_mul_f32_e32 v17, 0x4b800000, v16
	v_cmp_gt_f32_e64 s[2:3], s30, v16
	s_nop 1
	v_cndmask_b32_e64 v16, v16, v17, s[2:3]
	v_rsq_f32_e32 v28, v16
	v_lshlrev_b64 v[16:17], 12, v[142:143]
	v_lshl_add_u64 v[16:17], v[160:161], 0, v[16:17]
	v_add_u32_e32 v142, s6, v142
	v_mul_f32_e32 v29, 0x45800000, v28
	v_cndmask_b32_e64 v28, v28, v29, s[2:3]
	v_pk_mul_f32 v[18:19], v[18:19], v[28:29] op_sel_hi:[1,0]
	v_pk_mul_f32 v[24:25], v[24:25], v[28:29] op_sel_hi:[1,0]
	s_waitcnt vmcnt(0)
	v_pk_fma_f32 v[2:3], v[2:3], v[18:19], v[6:7]
	v_pk_fma_f32 v[4:5], v[4:5], v[24:25], v[8:9]
	global_store_dwordx4 v[16:17], v[2:5], off
	global_load_dwordx4 v[2:5], v[156:157], off offset:16
	s_nop 0
	global_load_dwordx4 v[6:9], v[158:159], off offset:16
	v_pk_mul_f32 v[18:19], v[20:21], v[28:29] op_sel_hi:[1,0]
	v_pk_mul_f32 v[20:21], v[26:27], v[28:29] op_sel_hi:[1,0]
	v_pk_mul_f32 v[10:11], v[10:11], v[28:29] op_sel_hi:[1,0]
	v_cmp_lt_i32_e64 s[2:3], s31, v142
	v_pk_mul_f32 v[12:13], v[12:13], v[28:29] op_sel_hi:[1,0]
	s_or_b64 s[10:11], s[2:3], s[10:11]
	s_waitcnt vmcnt(0)
	v_pk_fma_f32 v[2:3], v[2:3], v[18:19], v[6:7]
	v_pk_fma_f32 v[4:5], v[4:5], v[20:21], v[8:9]
	global_store_dwordx4 v[16:17], v[2:5], off offset:16
	global_load_dwordx4 v[2:5], v[156:157], off offset:32
	s_nop 0
	global_load_dwordx4 v[6:9], v[158:159], off offset:32
	v_pk_mul_f32 v[18:19], v[22:23], v[28:29] op_sel_hi:[1,0]
	s_waitcnt vmcnt(0)
	v_pk_fma_f32 v[4:5], v[4:5], v[10:11], v[8:9]
	v_pk_fma_f32 v[2:3], v[2:3], v[18:19], v[6:7]
	global_store_dwordx4 v[16:17], v[2:5], off offset:32
	global_load_dwordx4 v[2:5], v[156:157], off offset:48
	s_nop 0
	global_load_dwordx4 v[6:9], v[158:159], off offset:48
	v_pk_mul_f32 v[10:11], v[14:15], v[28:29] op_sel_hi:[1,0]
	s_waitcnt vmcnt(0)
	v_pk_fma_f32 v[4:5], v[12:13], v[4:5], v[8:9]
	v_pk_fma_f32 v[2:3], v[10:11], v[2:3], v[6:7]
	global_store_dwordx4 v[16:17], v[2:5], off offset:48
	s_andn2_b64 exec, exec, s[10:11]
	s_cbranch_execz .LBB0_3658

.LpB_kb:
	s_waitcnt vmcnt(0)
	s_cmp_lt_u32 s34, 8
	s_cselect_b64 s[2:3], -1, 0
	s_nop 0
	v_cndmask_b32_e64 v5, v212, v211, s[2:3]
	s_add_i32 s60, s33, 0
	v_readlane_b32 s16, v5, s60
	s_add_i32 s61, s33, 1
	v_readlane_b32 s18, v5, s61
	s_add_i32 s62, s33, 2
	v_readlane_b32 s35, v5, s62
	s_add_i32 s63, s33, 3
	v_readlane_b32 s36, v5, s63
	s_add_i32 s60, s33, 4
	v_readlane_b32 s20, v5, s60
	s_add_i32 s61, s33, 5
	v_readlane_b32 s22, v5, s61
	s_add_i32 s62, s33, 6
	v_readlane_b32 s24, v5, s62
	s_add_i32 s63, s33, 7
	v_readlane_b32 s26, v5, s63
	v_mad_u32_u24 v6, s16, v202, v138
	global_load_dwordx3 v[34:36], v6, s[80:81]
	v_mad_u32_u24 v8, s18, v202, v138
	global_load_dwordx3 v[44:46], v8, s[80:81]
	v_mad_u32_u24 v10, s35, v202, v138
	global_load_dwordx3 v[66:68], v10, s[80:81]
	v_mad_u32_u24 v12, s36, v202, v138
	global_load_dwordx3 v[40:42], v12, s[80:81]
	v_mad_u32_u24 v6, s20, v202, v138
	global_load_dwordx3 v[98:100], v6, s[80:81]
	v_mad_u32_u24 v8, s22, v202, v138
	global_load_dwordx3 v[72:74], v8, s[80:81]
	v_mad_u32_u24 v10, s24, v202, v138
	global_load_dwordx3 v[130:132], v10, s[80:81]
	v_mad_u32_u24 v12, s26, v202, v138
	global_load_dwordx3 v[104:106], v12, s[80:81]
	s_add_i32 s60, s33, 8
	v_readlane_b32 s16, v5, s60
	s_add_i32 s61, s33, 9
	v_readlane_b32 s18, v5, s61
	s_add_i32 s62, s33, 10
	v_readlane_b32 s35, v5, s62
	s_add_i32 s63, s33, 11
	v_readlane_b32 s36, v5, s63
	s_add_i32 s60, s33, 12
	v_readlane_b32 s20, v5, s60
	s_add_i32 s61, s33, 13
	v_readlane_b32 s22, v5, s61
	s_add_i32 s62, s33, 14
	v_readlane_b32 s24, v5, s62
	s_add_i32 s63, s33, 15
	v_readlane_b32 s26, v5, s63
	v_mad_u32_u24 v6, s16, v202, v138
	global_load_dwordx3 v[216:218], v6, s[80:81]
	v_mad_u32_u24 v8, s18, v202, v138
	global_load_dwordx3 v[220:222], v8, s[80:81]
	v_mad_u32_u24 v10, s35, v202, v138
	global_load_dwordx3 v[224:226], v10, s[80:81]
	v_mad_u32_u24 v12, s36, v202, v138
	global_load_dwordx3 v[228:230], v12, s[80:81]
	v_mad_u32_u24 v6, s20, v202, v138
	global_load_dwordx3 v[232:234], v6, s[80:81]
	v_mad_u32_u24 v8, s22, v202, v138
	global_load_dwordx3 v[236:238], v8, s[80:81]
	v_mad_u32_u24 v10, s24, v202, v138
	global_load_dwordx3 v[240:242], v10, s[80:81]
	v_mad_u32_u24 v12, s26, v202, v138
	global_load_dwordx3 v[244:246], v12, s[80:81]
	s_waitcnt vmcnt(8)
	s_cmp_lt_u32 s34, 8
	s_cselect_b64 s[2:3], -1, 0
	v_and_or_b32 v5, s33, 56, v231
	v_lshlrev_b32_e32 v5, 2, v5
	v_cndmask_b32_e64 v2, v214, v213, s[2:3]
	s_nop 0
	ds_bpermute_b32 v107, v5, v2
	s_waitcnt lgkmcnt(0)
	s_nop 0
	v_mov_b32_e32 v37, v44
	v_mov_b32_e32 v38, v45
	v_mov_b32_e32 v39, v46
	v_mov_b32_e32 v69, v40
	v_mov_b32_e32 v70, v41
	v_mov_b32_e32 v71, v42
	v_mov_b32_e32 v101, v72
	v_mov_b32_e32 v102, v73
	v_mov_b32_e32 v103, v74
	v_mov_b32_e32 v133, v104
	v_mov_b32_e32 v134, v105
	v_mov_b32_e32 v135, v106
	v_readlane_b32 s2, v107, 0
	v_readlane_b32 s14, v107, 1
	v_readlane_b32 s16, v107, 2
	v_readlane_b32 s18, v107, 3
	v_readlane_b32 s20, v107, 4
	v_readlane_b32 s22, v107, 5
	v_readlane_b32 s24, v107, 6
	v_readlane_b32 s26, v107, 7
	v_cvt_scalef32_pk32_f32_fp6 v[2:33], v[34:39], 1.0
	v_cvt_scalef32_pk32_f32_fp6 v[34:65], v[66:71], 1.0
	v_cvt_scalef32_pk32_f32_fp6 v[66:97], v[98:103], 1.0
	v_cvt_scalef32_pk32_f32_fp6 v[98:129], v[130:135], 1.0
	v_pk_fma_f32 v[178:179], v[2:3], s[2:3], v[178:179] op_sel_hi:[1,0,1]
	v_pk_fma_f32 v[176:177], v[4:5], s[2:3], v[176:177] op_sel_hi:[1,0,1]
	v_pk_fma_f32 v[174:175], v[6:7], s[2:3], v[174:175] op_sel_hi:[1,0,1]
	v_pk_fma_f32 v[172:173], v[8:9], s[2:3], v[172:173] op_sel_hi:[1,0,1]
	v_pk_fma_f32 v[170:171], v[10:11], s[2:3], v[170:171] op_sel_hi:[1,0,1]
	v_pk_fma_f32 v[168:169], v[12:13], s[2:3], v[168:169] op_sel_hi:[1,0,1]
	v_pk_fma_f32 v[166:167], v[14:15], s[2:3], v[166:167] op_sel_hi:[1,0,1]
	v_pk_fma_f32 v[180:181], v[16:17], s[2:3], v[180:181] op_sel_hi:[1,0,1]
	v_pk_fma_f32 v[178:179], v[18:19], s[14:15], v[178:179] op_sel_hi:[1,0,1]
	v_pk_fma_f32 v[176:177], v[20:21], s[14:15], v[176:177] op_sel_hi:[1,0,1]
	v_pk_fma_f32 v[174:175], v[22:23], s[14:15], v[174:175] op_sel_hi:[1,0,1]
	v_pk_fma_f32 v[172:173], v[24:25], s[14:15], v[172:173] op_sel_hi:[1,0,1]
	v_pk_fma_f32 v[170:171], v[26:27], s[14:15], v[170:171] op_sel_hi:[1,0,1]
	v_pk_fma_f32 v[168:169], v[28:29], s[14:15], v[168:169] op_sel_hi:[1,0,1]
	v_pk_fma_f32 v[166:167], v[30:31], s[14:15], v[166:167] op_sel_hi:[1,0,1]
	v_pk_fma_f32 v[180:181], v[32:33], s[14:15], v[180:181] op_sel_hi:[1,0,1]
	v_pk_fma_f32 v[178:179], v[34:35], s[16:17], v[178:179] op_sel_hi:[1,0,1]
	v_pk_fma_f32 v[176:177], v[36:37], s[16:17], v[176:177] op_sel_hi:[1,0,1]
	v_pk_fma_f32 v[174:175], v[38:39], s[16:17], v[174:175] op_sel_hi:[1,0,1]
	v_pk_fma_f32 v[172:173], v[40:41], s[16:17], v[172:173] op_sel_hi:[1,0,1]
	v_pk_fma_f32 v[170:171], v[42:43], s[16:17], v[170:171] op_sel_hi:[1,0,1]
	v_pk_fma_f32 v[168:169], v[44:45], s[16:17], v[168:169] op_sel_hi:[1,0,1]
	v_pk_fma_f32 v[166:167], v[46:47], s[16:17], v[166:167] op_sel_hi:[1,0,1]
	v_pk_fma_f32 v[180:181], v[48:49], s[16:17], v[180:181] op_sel_hi:[1,0,1]
	v_pk_fma_f32 v[178:179], v[50:51], s[18:19], v[178:179] op_sel_hi:[1,0,1]
	v_pk_fma_f32 v[176:177], v[52:53], s[18:19], v[176:177] op_sel_hi:[1,0,1]
	v_pk_fma_f32 v[174:175], v[54:55], s[18:19], v[174:175] op_sel_hi:[1,0,1]
	v_pk_fma_f32 v[172:173], v[56:57], s[18:19], v[172:173] op_sel_hi:[1,0,1]
	v_pk_fma_f32 v[170:171], v[58:59], s[18:19], v[170:171] op_sel_hi:[1,0,1]
	v_pk_fma_f32 v[168:169], v[60:61], s[18:19], v[168:169] op_sel_hi:[1,0,1]
	v_pk_fma_f32 v[166:167], v[62:63], s[18:19], v[166:167] op_sel_hi:[1,0,1]
	v_pk_fma_f32 v[180:181], v[64:65], s[18:19], v[180:181] op_sel_hi:[1,0,1]
	v_pk_fma_f32 v[178:179], v[66:67], s[20:21], v[178:179] op_sel_hi:[1,0,1]
	v_pk_fma_f32 v[176:177], v[68:69], s[20:21], v[176:177] op_sel_hi:[1,0,1]
	v_pk_fma_f32 v[174:175], v[70:71], s[20:21], v[174:175] op_sel_hi:[1,0,1]
	v_pk_fma_f32 v[172:173], v[72:73], s[20:21], v[172:173] op_sel_hi:[1,0,1]
	v_pk_fma_f32 v[170:171], v[74:75], s[20:21], v[170:171] op_sel_hi:[1,0,1]
	v_pk_fma_f32 v[168:169], v[76:77], s[20:21], v[168:169] op_sel_hi:[1,0,1]
	v_pk_fma_f32 v[166:167], v[78:79], s[20:21], v[166:167] op_sel_hi:[1,0,1]
	v_pk_fma_f32 v[180:181], v[80:81], s[20:21], v[180:181] op_sel_hi:[1,0,1]
	v_pk_fma_f32 v[178:179], v[82:83], s[22:23], v[178:179] op_sel_hi:[1,0,1]
	v_pk_fma_f32 v[176:177], v[84:85], s[22:23], v[176:177] op_sel_hi:[1,0,1]
	v_pk_fma_f32 v[174:175], v[86:87], s[22:23], v[174:175] op_sel_hi:[1,0,1]
	v_pk_fma_f32 v[172:173], v[88:89], s[22:23], v[172:173] op_sel_hi:[1,0,1]
	v_pk_fma_f32 v[170:171], v[90:91], s[22:23], v[170:171] op_sel_hi:[1,0,1]
	v_pk_fma_f32 v[168:169], v[92:93], s[22:23], v[168:169] op_sel_hi:[1,0,1]
	v_pk_fma_f32 v[166:167], v[94:95], s[22:23], v[166:167] op_sel_hi:[1,0,1]
	v_pk_fma_f32 v[180:181], v[96:97], s[22:23], v[180:181] op_sel_hi:[1,0,1]
	v_pk_fma_f32 v[178:179], v[98:99], s[24:25], v[178:179] op_sel_hi:[1,0,1]
	v_pk_fma_f32 v[176:177], v[100:101], s[24:25], v[176:177] op_sel_hi:[1,0,1]
	v_pk_fma_f32 v[174:175], v[102:103], s[24:25], v[174:175] op_sel_hi:[1,0,1]
	v_pk_fma_f32 v[172:173], v[104:105], s[24:25], v[172:173] op_sel_hi:[1,0,1]
	v_pk_fma_f32 v[170:171], v[106:107], s[24:25], v[170:171] op_sel_hi:[1,0,1]
	v_pk_fma_f32 v[168:169], v[108:109], s[24:25], v[168:169] op_sel_hi:[1,0,1]
	v_pk_fma_f32 v[166:167], v[110:111], s[24:25], v[166:167] op_sel_hi:[1,0,1]
	v_pk_fma_f32 v[180:181], v[112:113], s[24:25], v[180:181] op_sel_hi:[1,0,1]
	v_pk_fma_f32 v[178:179], v[114:115], s[26:27], v[178:179] op_sel_hi:[1,0,1]
	v_pk_fma_f32 v[176:177], v[116:117], s[26:27], v[176:177] op_sel_hi:[1,0,1]
	v_pk_fma_f32 v[174:175], v[118:119], s[26:27], v[174:175] op_sel_hi:[1,0,1]
	v_pk_fma_f32 v[172:173], v[120:121], s[26:27], v[172:173] op_sel_hi:[1,0,1]
	v_pk_fma_f32 v[170:171], v[122:123], s[26:27], v[170:171] op_sel_hi:[1,0,1]
	v_pk_fma_f32 v[168:169], v[124:125], s[26:27], v[168:169] op_sel_hi:[1,0,1]
	v_pk_fma_f32 v[166:167], v[126:127], s[26:27], v[166:167] op_sel_hi:[1,0,1]
	v_pk_fma_f32 v[180:181], v[128:129], s[26:27], v[180:181] op_sel_hi:[1,0,1]
	s_add_i32 s34, s34, 1
	s_add_i32 s33, s33, 8
	s_waitcnt vmcnt(0)
	s_cmp_lt_u32 s34, 8
	s_cselect_b64 s[2:3], -1, 0
	v_and_or_b32 v5, s33, 56, v231
	v_lshlrev_b32_e32 v5, 2, v5
	v_cndmask_b32_e64 v2, v214, v213, s[2:3]
	s_nop 0
	ds_bpermute_b32 v107, v5, v2
	s_waitcnt lgkmcnt(0)
	s_nop 0
	v_mov_b32_e32 v219, v220
	v_mov_b32_e32 v220, v221
	v_mov_b32_e32 v221, v222
	v_mov_b32_e32 v227, v228
	v_mov_b32_e32 v228, v229
	v_mov_b32_e32 v229, v230
	v_mov_b32_e32 v235, v236
	v_mov_b32_e32 v236, v237
	v_mov_b32_e32 v237, v238
	v_mov_b32_e32 v243, v244
	v_mov_b32_e32 v244, v245
	v_mov_b32_e32 v245, v246
	v_readlane_b32 s2, v107, 0
	v_readlane_b32 s14, v107, 1
	v_readlane_b32 s16, v107, 2
	v_readlane_b32 s18, v107, 3
	v_readlane_b32 s20, v107, 4
	v_readlane_b32 s22, v107, 5
	v_readlane_b32 s24, v107, 6
	v_readlane_b32 s26, v107, 7
	v_cvt_scalef32_pk32_f32_fp6 v[2:33], v[216:221], 1.0
	v_cvt_scalef32_pk32_f32_fp6 v[34:65], v[224:229], 1.0
	v_cvt_scalef32_pk32_f32_fp6 v[66:97], v[232:237], 1.0
	v_cvt_scalef32_pk32_f32_fp6 v[98:129], v[240:245], 1.0
	v_pk_fma_f32 v[178:179], v[2:3], s[2:3], v[178:179] op_sel_hi:[1,0,1]
	v_pk_fma_f32 v[176:177], v[4:5], s[2:3], v[176:177] op_sel_hi:[1,0,1]
	v_pk_fma_f32 v[174:175], v[6:7], s[2:3], v[174:175] op_sel_hi:[1,0,1]
	v_pk_fma_f32 v[172:173], v[8:9], s[2:3], v[172:173] op_sel_hi:[1,0,1]
	v_pk_fma_f32 v[170:171], v[10:11], s[2:3], v[170:171] op_sel_hi:[1,0,1]
	v_pk_fma_f32 v[168:169], v[12:13], s[2:3], v[168:169] op_sel_hi:[1,0,1]
	v_pk_fma_f32 v[166:167], v[14:15], s[2:3], v[166:167] op_sel_hi:[1,0,1]
	v_pk_fma_f32 v[180:181], v[16:17], s[2:3], v[180:181] op_sel_hi:[1,0,1]
	v_pk_fma_f32 v[178:179], v[18:19], s[14:15], v[178:179] op_sel_hi:[1,0,1]
	v_pk_fma_f32 v[176:177], v[20:21], s[14:15], v[176:177] op_sel_hi:[1,0,1]
	v_pk_fma_f32 v[174:175], v[22:23], s[14:15], v[174:175] op_sel_hi:[1,0,1]
	v_pk_fma_f32 v[172:173], v[24:25], s[14:15], v[172:173] op_sel_hi:[1,0,1]
	v_pk_fma_f32 v[170:171], v[26:27], s[14:15], v[170:171] op_sel_hi:[1,0,1]
	v_pk_fma_f32 v[168:169], v[28:29], s[14:15], v[168:169] op_sel_hi:[1,0,1]
	v_pk_fma_f32 v[166:167], v[30:31], s[14:15], v[166:167] op_sel_hi:[1,0,1]
	v_pk_fma_f32 v[180:181], v[32:33], s[14:15], v[180:181] op_sel_hi:[1,0,1]
	v_pk_fma_f32 v[178:179], v[34:35], s[16:17], v[178:179] op_sel_hi:[1,0,1]
	v_pk_fma_f32 v[176:177], v[36:37], s[16:17], v[176:177] op_sel_hi:[1,0,1]
	v_pk_fma_f32 v[174:175], v[38:39], s[16:17], v[174:175] op_sel_hi:[1,0,1]
	v_pk_fma_f32 v[172:173], v[40:41], s[16:17], v[172:173] op_sel_hi:[1,0,1]
	v_pk_fma_f32 v[170:171], v[42:43], s[16:17], v[170:171] op_sel_hi:[1,0,1]
	v_pk_fma_f32 v[168:169], v[44:45], s[16:17], v[168:169] op_sel_hi:[1,0,1]
	v_pk_fma_f32 v[166:167], v[46:47], s[16:17], v[166:167] op_sel_hi:[1,0,1]
	v_pk_fma_f32 v[180:181], v[48:49], s[16:17], v[180:181] op_sel_hi:[1,0,1]
	v_pk_fma_f32 v[178:179], v[50:51], s[18:19], v[178:179] op_sel_hi:[1,0,1]
	v_pk_fma_f32 v[176:177], v[52:53], s[18:19], v[176:177] op_sel_hi:[1,0,1]
	v_pk_fma_f32 v[174:175], v[54:55], s[18:19], v[174:175] op_sel_hi:[1,0,1]
	v_pk_fma_f32 v[172:173], v[56:57], s[18:19], v[172:173] op_sel_hi:[1,0,1]
	v_pk_fma_f32 v[170:171], v[58:59], s[18:19], v[170:171] op_sel_hi:[1,0,1]
	v_pk_fma_f32 v[168:169], v[60:61], s[18:19], v[168:169] op_sel_hi:[1,0,1]
	v_pk_fma_f32 v[166:167], v[62:63], s[18:19], v[166:167] op_sel_hi:[1,0,1]
	v_pk_fma_f32 v[180:181], v[64:65], s[18:19], v[180:181] op_sel_hi:[1,0,1]
	v_pk_fma_f32 v[178:179], v[66:67], s[20:21], v[178:179] op_sel_hi:[1,0,1]
	v_pk_fma_f32 v[176:177], v[68:69], s[20:21], v[176:177] op_sel_hi:[1,0,1]
	v_pk_fma_f32 v[174:175], v[70:71], s[20:21], v[174:175] op_sel_hi:[1,0,1]
	v_pk_fma_f32 v[172:173], v[72:73], s[20:21], v[172:173] op_sel_hi:[1,0,1]
	v_pk_fma_f32 v[170:171], v[74:75], s[20:21], v[170:171] op_sel_hi:[1,0,1]
	v_pk_fma_f32 v[168:169], v[76:77], s[20:21], v[168:169] op_sel_hi:[1,0,1]
	v_pk_fma_f32 v[166:167], v[78:79], s[20:21], v[166:167] op_sel_hi:[1,0,1]
	v_pk_fma_f32 v[180:181], v[80:81], s[20:21], v[180:181] op_sel_hi:[1,0,1]
	v_pk_fma_f32 v[178:179], v[82:83], s[22:23], v[178:179] op_sel_hi:[1,0,1]
	v_pk_fma_f32 v[176:177], v[84:85], s[22:23], v[176:177] op_sel_hi:[1,0,1]
	v_pk_fma_f32 v[174:175], v[86:87], s[22:23], v[174:175] op_sel_hi:[1,0,1]
	v_pk_fma_f32 v[172:173], v[88:89], s[22:23], v[172:173] op_sel_hi:[1,0,1]
	v_pk_fma_f32 v[170:171], v[90:91], s[22:23], v[170:171] op_sel_hi:[1,0,1]
	v_pk_fma_f32 v[168:169], v[92:93], s[22:23], v[168:169] op_sel_hi:[1,0,1]
	v_pk_fma_f32 v[166:167], v[94:95], s[22:23], v[166:167] op_sel_hi:[1,0,1]
	v_pk_fma_f32 v[180:181], v[96:97], s[22:23], v[180:181] op_sel_hi:[1,0,1]
	v_pk_fma_f32 v[178:179], v[98:99], s[24:25], v[178:179] op_sel_hi:[1,0,1]
	v_pk_fma_f32 v[176:177], v[100:101], s[24:25], v[176:177] op_sel_hi:[1,0,1]
	v_pk_fma_f32 v[174:175], v[102:103], s[24:25], v[174:175] op_sel_hi:[1,0,1]
	v_pk_fma_f32 v[172:173], v[104:105], s[24:25], v[172:173] op_sel_hi:[1,0,1]
	v_pk_fma_f32 v[170:171], v[106:107], s[24:25], v[170:171] op_sel_hi:[1,0,1]
	v_pk_fma_f32 v[168:169], v[108:109], s[24:25], v[168:169] op_sel_hi:[1,0,1]
	v_pk_fma_f32 v[166:167], v[110:111], s[24:25], v[166:167] op_sel_hi:[1,0,1]
	v_pk_fma_f32 v[180:181], v[112:113], s[24:25], v[180:181] op_sel_hi:[1,0,1]
	v_pk_fma_f32 v[178:179], v[114:115], s[26:27], v[178:179] op_sel_hi:[1,0,1]
	v_pk_fma_f32 v[176:177], v[116:117], s[26:27], v[176:177] op_sel_hi:[1,0,1]
	v_pk_fma_f32 v[174:175], v[118:119], s[26:27], v[174:175] op_sel_hi:[1,0,1]
	v_pk_fma_f32 v[172:173], v[120:121], s[26:27], v[172:173] op_sel_hi:[1,0,1]
	v_pk_fma_f32 v[170:171], v[122:123], s[26:27], v[170:171] op_sel_hi:[1,0,1]
	v_pk_fma_f32 v[168:169], v[124:125], s[26:27], v[168:169] op_sel_hi:[1,0,1]
	v_pk_fma_f32 v[166:167], v[126:127], s[26:27], v[166:167] op_sel_hi:[1,0,1]
	v_pk_fma_f32 v[180:181], v[128:129], s[26:27], v[180:181] op_sel_hi:[1,0,1]
	s_add_i32 s34, s34, 1
	s_add_i32 s33, s33, 8
	s_cmpk_lg_i32 s33, 0x80
	s_cbranch_scc1 .LpB_kb
	s_branch .LpB_epi
